# start-up: no L2 write-back before the ready flag (barrier words are zeroed with write-through stores and drained)
# speedup vs baseline: 1.0038x; 1.0020x over previous
.LBB0_6:
	v_lshrrev_b32_e32 v1, 20, v0
	v_lshrrev_b32_e32 v0, 10, v0
	s_waitcnt vmcnt(0) lgkmcnt(0)
	v_or_b32_e32 v0, v0, v1
	s_movk_i32 s2, 0x3ff
	v_and_or_b32 v0, v0, s2, v175
	v_cmp_eq_u32_e32 vcc, 0, v0
	s_waitcnt lgkmcnt(0)
	s_barrier
	s_and_saveexec_b64 s[2:3], vcc
	s_cbranch_execz .LBB0_16
	v_readlane_b32 s6, v253, 0
	v_mov_b32_e32 v2, 0x4000
	s_mov_b32 s7, 0x5afec0de
	s_mov_b32 s8, 0x1eedbeef
	s_cmp_lg_u32 s6, 0
	s_cbranch_scc1 .Lrdy_wait
	v_mov_b32_e32 v4, s7
	v_mov_b32_e32 v5, s8
	global_store_dwordx2 v2, v[4:5], s[88:89] sc0 sc1
	s_waitcnt vmcnt(0)
	s_branch .Lrdy_done
